# diff item: closing workgroup barrier removed (the following work-fetch barrier orders the same LDS accesses)
# speedup vs baseline: 1.0077x; 1.0077x over previous
; DI void diff_item(const Params& P, char* lds, int layer, int pair, int qt, int& tab_head) {
;     ...
;     __syncthreads();
; DI void phase_att(const Params& P, char* lds, int hb, int layer) {
;     ...
;         while (true) {
;             if (tid == 0) *slot = (int)atomicAdd(&ctr[qx], 1u);
;             __syncthreads();
;             const int qi = *slot;
.LBB0_197:
	s_or_b64 exec, exec, s[40:41]
	s_mov_b32 s49, s3
	s_waitcnt lgkmcnt(0)
.LBB0_198:
	s_andn2_b64 vcc, exec, s[38:39]
	s_cbranch_vccz .LBB0_195
